# EpiSwiglu: hand-interleaved silu chains (8 wide), pad nops removed
# speedup vs baseline: 1.0104x; 1.0104x over previous
; #define PG8_STAGE(bufoff, gbase, voff) do { _Pragma("unroll") for (int _i = 0; _i < 2; ++_i) \
;         __builtin_amdgcn_global_load_lds((const unsigned*)((const char*)(gbase) + (voff)[_i]), (LAS unsigned*)(lds + (bufoff) + ldsw + _i * 8192), 16, 0, 0); } while (0)
; #define PG8_LDA(dst, b, h) do { _Pragma("unroll") for (int m = 0; m < 4; ++m) _Pragma("unroll") for (int k = 0; k < 2; ++k) dst[m][k] = *(const LAS bf16x8*)(lds + PG8_SA(b, h) + aoff + m * 2048 + k * 1024); } while (0)
; #define PG8_LDB(dst, b, h) do { _Pragma("unroll") for (int n = 0; n < 2; ++n) _Pragma("unroll") for (int k = 0; k < 2; ++k) dst[n][k] = *(const LAS bf16x8*)(lds + PG8_SB(b, h) + boff + n * 2048 + k * 1024); } while (0)
; #define PG8_MMA(ai, bj, At, Bt) do { __builtin_amdgcn_s_setprio(1); _Pragma("unroll") for (int m = 0; m < 4; ++m) _Pragma("unroll") for (int n = 0; n < 2; ++n) _Pragma("unroll") for (int k = 0; k < 2; ++k) \
;         acc[ai][bj][m][n] = __builtin_amdgcn_mfma_f32_16x16x32_bf16(Bt[n][k], At[m][k], acc[ai][bj][m][n], 0, 0, 0); __builtin_amdgcn_s_setprio(0); } while (0)
; #define PG8_WAIT_V(n) asm volatile("s_waitcnt vmcnt(" #n ")" ::: "memory")
; #define PG8_WAIT_L(n) asm volatile("s_waitcnt lgkmcnt(" #n ")" ::: "memory")
; #define PG8_BAR __builtin_amdgcn_s_barrier()
; #define PG8_SCHED __builtin_amdgcn_sched_barrier(0)
; template <class Epi, class Sched>
; DI void gemm_phase(LAS unsigned char* lds, const Gemm g, const Sched& S, const Epi& E) {
;     ...
;             PG8_LDB(B0, 0, 0); PG8_SCHED; PG8_LDA(At, 0, 0); PG8_STAGE(PG8_SA(1, 1), a1 + hstep, voffA);
;             PG8_WAIT_L(8); PG8_BAR; PG8_WAIT_L(0); PG8_MMA(0, 0, At, B0); PG8_BAR; PG8_SCHED;
;             PG8_LDB(B1, 0, 1); PG8_STAGE(PG8_SB(0, 0), b2, voffB);
;             PG8_BAR; PG8_WAIT_L(0); PG8_MMA(0, 1, At, B1); PG8_BAR;
;             PG8_LDA(At, 0, 1); PG8_STAGE(PG8_SA(0, 0), a2, voffA);
;             PG8_BAR; PG8_WAIT_L(0); PG8_MMA(1, 0, At, B0); PG8_BAR; PG8_SCHED;
;             PG8_STAGE(PG8_SB(0, 1), b2 + hstep, voffB);
;             PG8_WAIT_V(6); PG8_BAR; PG8_MMA(1, 1, At, B1); PG8_BAR;
.LBB0_1840:
	s_add_u32 s0, s22, 0xfffc0080
	s_addc_u32 s1, s23, -1
	s_add_i32 s46, 0, 0x10000
	v_add_u32_e32 v144, s46, v147
	ds_read_b128 v[140:143], v144
	ds_read_b128 v[152:155], v144 offset:1024
	ds_read_b128 v[156:159], v144 offset:2048
	ds_read_b128 v[160:163], v144 offset:3072
	s_cmp_eq_u32 s45, 12
	s_cselect_b32 s39, s15, s1
	s_cselect_b32 s38, s34, s0
	s_cselect_b32 s25, s13, s44
	s_cselect_b32 s24, s42, s43
	v_lshl_add_u64 v[144:145], s[22:23], 0, v[136:137]
	s_add_i32 m0, s26, 0xc000
	ds_read_b128 v[164:167], v150
	ds_read_b128 v[168:171], v150 offset:1024
	ds_read_b128 v[172:175], v150 offset:2048
	ds_read_b128 v[176:179], v150 offset:3072
	ds_read_b128 v[180:183], v150 offset:4096
	ds_read_b128 v[184:187], v150 offset:5120
	ds_read_b128 v[188:191], v150 offset:6144
	ds_read_b128 v[192:195], v150 offset:7168
	global_load_lds_dwordx4 v[144:145], off
	v_lshl_add_u64 v[144:145], s[22:23], 0, v[138:139]
	s_add_i32 m0, s26, 0xe000
	s_nop 0
	global_load_lds_dwordx4 v[144:145], off
	s_waitcnt lgkmcnt(8)
	s_barrier
	s_waitcnt lgkmcnt(0)
	s_setprio 1
	s_waitcnt lgkmcnt(0)
	v_mfma_f32_16x16x32_bf16 v[126:129], v[140:143], v[164:167], v[126:129]
	v_mfma_f32_16x16x32_bf16 v[122:125], v[156:159], v[164:167], v[122:125]
	v_mfma_f32_16x16x32_bf16 v[110:113], v[140:143], v[172:175], v[110:113]
	v_mfma_f32_16x16x32_bf16 v[106:109], v[156:159], v[172:175], v[106:109]
	v_mfma_f32_16x16x32_bf16 v[92:95], v[140:143], v[180:183], v[92:95]
	v_mfma_f32_16x16x32_bf16 v[88:91], v[156:159], v[180:183], v[88:91]
	v_mfma_f32_16x16x32_bf16 v[76:79], v[140:143], v[188:191], v[76:79]
	v_mfma_f32_16x16x32_bf16 v[72:75], v[156:159], v[188:191], v[72:75]
	v_mfma_f32_16x16x32_bf16 v[126:129], v[152:155], v[168:171], v[126:129]
	v_mfma_f32_16x16x32_bf16 v[122:125], v[160:163], v[168:171], v[122:125]
	v_mfma_f32_16x16x32_bf16 v[110:113], v[152:155], v[176:179], v[110:113]
	v_mfma_f32_16x16x32_bf16 v[106:109], v[160:163], v[176:179], v[106:109]
	v_mfma_f32_16x16x32_bf16 v[92:95], v[152:155], v[184:187], v[92:95]
	v_mfma_f32_16x16x32_bf16 v[88:91], v[160:163], v[184:187], v[88:91]
	v_mfma_f32_16x16x32_bf16 v[76:79], v[152:155], v[192:195], v[76:79]
	v_mfma_f32_16x16x32_bf16 v[72:75], v[160:163], v[192:195], v[72:75]
	s_setprio 0
	s_barrier
	s_add_i32 s47, 0, 0x14000
	v_add_u32_e32 v144, s47, v147
	s_add_i32 s0, s46, s7
	ds_read_b128 v[196:199], v144
	ds_read_b128 v[200:203], v144 offset:1024
	ds_read_b128 v[204:207], v144 offset:2048
	ds_read_b128 v[208:211], v144 offset:3072
	v_lshl_add_u64 v[144:145], s[24:25], 0, v[96:97]
	s_mov_b32 m0, s0
	v_lshl_add_u64 v[212:213], s[24:25], 0, v[134:135]
	global_load_lds_dwordx4 v[144:145], off
	s_add_i32 m0, s0, 0x2000
	s_nop 0
	global_load_lds_dwordx4 v[212:213], off
	s_barrier
	s_waitcnt lgkmcnt(0)
	s_setprio 1
	s_waitcnt lgkmcnt(0)
	v_mfma_f32_16x16x32_bf16 v[118:121], v[196:199], v[164:167], v[118:121]
	v_mfma_f32_16x16x32_bf16 v[114:117], v[204:207], v[164:167], v[114:117]
	v_mfma_f32_16x16x32_bf16 v[102:105], v[196:199], v[172:175], v[102:105]
	v_mfma_f32_16x16x32_bf16 v[98:101], v[204:207], v[172:175], v[98:101]
	v_mfma_f32_16x16x32_bf16 v[84:87], v[196:199], v[180:183], v[84:87]
	v_mfma_f32_16x16x32_bf16 v[80:83], v[204:207], v[180:183], v[80:83]
	v_mfma_f32_16x16x32_bf16 v[68:71], v[196:199], v[188:191], v[68:71]
	v_mfma_f32_16x16x32_bf16 v[64:67], v[204:207], v[188:191], v[64:67]
	v_mfma_f32_16x16x32_bf16 v[118:121], v[200:203], v[168:171], v[118:121]
	v_mfma_f32_16x16x32_bf16 v[114:117], v[208:211], v[168:171], v[114:117]
	v_mfma_f32_16x16x32_bf16 v[102:105], v[200:203], v[176:179], v[102:105]
	v_mfma_f32_16x16x32_bf16 v[98:101], v[208:211], v[176:179], v[98:101]
	v_mfma_f32_16x16x32_bf16 v[84:87], v[200:203], v[184:187], v[84:87]
	v_mfma_f32_16x16x32_bf16 v[80:83], v[208:211], v[184:187], v[80:83]
	v_mfma_f32_16x16x32_bf16 v[68:71], v[200:203], v[192:195], v[68:71]
	v_mfma_f32_16x16x32_bf16 v[64:67], v[208:211], v[192:195], v[64:67]
	s_setprio 0
	s_mov_b32 m0, s26
	v_lshl_add_u64 v[214:215], s[38:39], 0, v[130:131]
	s_barrier
	ds_read_b128 v[164:167], v150 offset:16384
	ds_read_b128 v[168:171], v150 offset:17408
	ds_read_b128 v[172:175], v150 offset:18432
	ds_read_b128 v[176:179], v150 offset:19456
	ds_read_b128 v[180:183], v150 offset:20480
	ds_read_b128 v[184:187], v150 offset:21504
	ds_read_b128 v[188:191], v150 offset:22528
	ds_read_b128 v[192:195], v150 offset:23552
	global_load_lds_dwordx4 v[214:215], off
	v_lshl_add_u64 v[216:217], s[38:39], 0, v[132:133]
	s_mov_b32 m0, s27
	s_nop 0
	global_load_lds_dwordx4 v[216:217], off
	s_barrier
	s_waitcnt lgkmcnt(0)
	s_setprio 1
	s_waitcnt lgkmcnt(0)
	v_mfma_f32_16x16x32_bf16 v[60:63], v[140:143], v[164:167], v[60:63]
	v_mfma_f32_16x16x32_bf16 v[56:59], v[156:159], v[164:167], v[56:59]
	v_mfma_f32_16x16x32_bf16 v[44:47], v[140:143], v[172:175], v[44:47]
	v_mfma_f32_16x16x32_bf16 v[40:43], v[156:159], v[172:175], v[40:43]
	v_mfma_f32_16x16x32_bf16 v[28:31], v[140:143], v[180:183], v[28:31]
	v_mfma_f32_16x16x32_bf16 v[24:27], v[156:159], v[180:183], v[24:27]
	v_mfma_f32_16x16x32_bf16 v[12:15], v[140:143], v[188:191], v[12:15]
	v_mfma_f32_16x16x32_bf16 v[8:11], v[156:159], v[188:191], v[8:11]
	v_mfma_f32_16x16x32_bf16 v[60:63], v[152:155], v[168:171], v[60:63]
	v_mfma_f32_16x16x32_bf16 v[56:59], v[160:163], v[168:171], v[56:59]
	v_mfma_f32_16x16x32_bf16 v[44:47], v[152:155], v[176:179], v[44:47]
	v_mfma_f32_16x16x32_bf16 v[40:43], v[160:163], v[176:179], v[40:43]
	v_mfma_f32_16x16x32_bf16 v[28:31], v[152:155], v[184:187], v[28:31]
	v_mfma_f32_16x16x32_bf16 v[24:27], v[160:163], v[184:187], v[24:27]
	v_mfma_f32_16x16x32_bf16 v[12:15], v[152:155], v[192:195], v[12:15]
	v_mfma_f32_16x16x32_bf16 v[8:11], v[160:163], v[192:195], v[8:11]
	s_setprio 0
	s_barrier
; #define PG8_STAGE(bufoff, gbase, voff) do { _Pragma("unroll") for (int _i = 0; _i < 2; ++_i) \
;         __builtin_amdgcn_global_load_lds((const unsigned*)((const char*)(gbase) + (voff)[_i]), (LAS unsigned*)(lds + (bufoff) + ldsw + _i * 8192), 16, 0, 0); } while (0)
; #define PG8_LDA(dst, b, h) do { _Pragma("unroll") for (int m = 0; m < 4; ++m) _Pragma("unroll") for (int k = 0; k < 2; ++k) dst[m][k] = *(const LAS bf16x8*)(lds + PG8_SA(b, h) + aoff + m * 2048 + k * 1024); } while (0)
; #define PG8_LDB(dst, b, h) do { _Pragma("unroll") for (int n = 0; n < 2; ++n) _Pragma("unroll") for (int k = 0; k < 2; ++k) dst[n][k] = *(const LAS bf16x8*)(lds + PG8_SB(b, h) + boff + n * 2048 + k * 1024); } while (0)
; #define PG8_MMA(ai, bj, At, Bt) do { __builtin_amdgcn_s_setprio(1); _Pragma("unroll") for (int m = 0; m < 4; ++m) _Pragma("unroll") for (int n = 0; n < 2; ++n) _Pragma("unroll") for (int k = 0; k < 2; ++k) \
;         acc[ai][bj][m][n] = __builtin_amdgcn_mfma_f32_16x16x32_bf16(Bt[n][k], At[m][k], acc[ai][bj][m][n], 0, 0, 0); __builtin_amdgcn_s_setprio(0); } while (0)
; #define PG8_WAIT_V(n) asm volatile("s_waitcnt vmcnt(" #n ")" ::: "memory")
; #define PG8_WAIT_L(n) asm volatile("s_waitcnt lgkmcnt(" #n ")" ::: "memory")
; #define PG8_BAR __builtin_amdgcn_s_barrier()
; #define PG8_SCHED __builtin_amdgcn_sched_barrier(0)
; template <class Epi, class Sched>
; DI void gemm_phase(LAS unsigned char* lds, const Gemm g, const Sched& S, const Epi& E) {
;     ...
;             PG8_WAIT_V(6); PG8_BAR; PG8_MMA(1, 1, At, B1); PG8_BAR;
;             PG8_LDB(B0, 1, 0); PG8_SCHED; PG8_LDA(At, 1, 0); PG8_STAGE(PG8_SA(0, 1), a2 + hstep, voffA);
;             PG8_WAIT_L(8); PG8_BAR; PG8_WAIT_L(0); PG8_MMA(0, 0, At, B0); PG8_BAR; PG8_SCHED;
;             PG8_LDB(B1, 1, 1); PG8_STAGE(PG8_SB(1, 0), b3, voffB);
;             PG8_BAR; PG8_WAIT_L(0); PG8_MMA(0, 1, At, B1); PG8_BAR;
;             PG8_LDA(At, 1, 1); PG8_STAGE(PG8_SA(1, 0), a3, voffA);
;             PG8_BAR; PG8_WAIT_L(0); PG8_MMA(1, 0, At, B0); PG8_BAR; PG8_SCHED;
	s_add_u32 s0, s24, 0x40000
	s_addc_u32 s1, s25, 0
	s_add_i32 s46, s47, s7
	v_lshl_add_u64 v[140:141], s[0:1], 0, v[96:97]
	s_mov_b32 m0, s46
	s_nop 0
	global_load_lds_dwordx4 v[140:141], off
	v_lshl_add_u64 v[140:141], s[0:1], 0, v[134:135]
	s_add_i32 m0, s46, 0x2000
	s_nop 0
	global_load_lds_dwordx4 v[140:141], off
	s_waitcnt vmcnt(6)
	s_barrier
	s_setprio 1
	v_mfma_f32_16x16x32_bf16 v[52:55], v[196:199], v[164:167], v[52:55]
	v_mfma_f32_16x16x32_bf16 v[48:51], v[204:207], v[164:167], v[48:51]
	v_mfma_f32_16x16x32_bf16 v[36:39], v[196:199], v[172:175], v[36:39]
	v_mfma_f32_16x16x32_bf16 v[32:35], v[204:207], v[172:175], v[32:35]
	v_mfma_f32_16x16x32_bf16 v[20:23], v[196:199], v[180:183], v[20:23]
	v_mfma_f32_16x16x32_bf16 v[16:19], v[204:207], v[180:183], v[16:19]
	v_mfma_f32_16x16x32_bf16 v[4:7], v[196:199], v[188:191], v[4:7]
	v_mfma_f32_16x16x32_bf16 v[0:3], v[204:207], v[188:191], v[0:3]
	v_mfma_f32_16x16x32_bf16 v[52:55], v[200:203], v[168:171], v[52:55]
	v_mfma_f32_16x16x32_bf16 v[48:51], v[208:211], v[168:171], v[48:51]
	v_mfma_f32_16x16x32_bf16 v[36:39], v[200:203], v[176:179], v[36:39]
	v_mfma_f32_16x16x32_bf16 v[32:35], v[208:211], v[176:179], v[32:35]
	v_mfma_f32_16x16x32_bf16 v[20:23], v[200:203], v[184:187], v[20:23]
	v_mfma_f32_16x16x32_bf16 v[16:19], v[208:211], v[184:187], v[16:19]
	v_mfma_f32_16x16x32_bf16 v[4:7], v[200:203], v[192:195], v[4:7]
	v_mfma_f32_16x16x32_bf16 v[0:3], v[208:211], v[192:195], v[0:3]
	s_setprio 0
	s_add_i32 s46, 0, 0x18000
	v_add_u32_e32 v151, s46, v147
	s_barrier
	ds_read_b128 v[140:143], v151
	ds_read_b128 v[152:155], v151 offset:1024
	ds_read_b128 v[156:159], v151 offset:2048
	ds_read_b128 v[160:163], v151 offset:3072
	s_add_u32 s0, s38, 0x40000
	s_addc_u32 s1, s39, 0
	s_mov_b32 m0, s28
	v_lshl_add_u64 v[196:197], s[0:1], 0, v[130:131]
	ds_read_b128 v[164:167], v150 offset:32768
	ds_read_b128 v[168:171], v150 offset:33792
	ds_read_b128 v[172:175], v150 offset:34816
	ds_read_b128 v[176:179], v150 offset:35840
	ds_read_b128 v[180:183], v150 offset:36864
	ds_read_b128 v[184:187], v150 offset:37888
	ds_read_b128 v[188:191], v150 offset:38912
	ds_read_b128 v[192:195], v150 offset:39936
	global_load_lds_dwordx4 v[196:197], off
	v_lshl_add_u64 v[196:197], s[0:1], 0, v[132:133]
	s_mov_b32 m0, s29
	s_nop 0
	global_load_lds_dwordx4 v[196:197], off
	s_waitcnt lgkmcnt(8)
	s_barrier
	s_waitcnt lgkmcnt(0)
	s_setprio 1
	s_waitcnt lgkmcnt(0)
	v_mfma_f32_16x16x32_bf16 v[126:129], v[140:143], v[164:167], v[126:129]
	v_mfma_f32_16x16x32_bf16 v[122:125], v[156:159], v[164:167], v[122:125]
	v_mfma_f32_16x16x32_bf16 v[110:113], v[140:143], v[172:175], v[110:113]
	v_mfma_f32_16x16x32_bf16 v[106:109], v[156:159], v[172:175], v[106:109]
	v_mfma_f32_16x16x32_bf16 v[92:95], v[140:143], v[180:183], v[92:95]
	v_mfma_f32_16x16x32_bf16 v[88:91], v[156:159], v[180:183], v[88:91]
	v_mfma_f32_16x16x32_bf16 v[76:79], v[140:143], v[188:191], v[76:79]
	v_mfma_f32_16x16x32_bf16 v[72:75], v[156:159], v[188:191], v[72:75]
	v_mfma_f32_16x16x32_bf16 v[126:129], v[152:155], v[168:171], v[126:129]
	v_mfma_f32_16x16x32_bf16 v[122:125], v[160:163], v[168:171], v[122:125]
	v_mfma_f32_16x16x32_bf16 v[110:113], v[152:155], v[176:179], v[110:113]
	v_mfma_f32_16x16x32_bf16 v[106:109], v[160:163], v[176:179], v[106:109]
	v_mfma_f32_16x16x32_bf16 v[92:95], v[152:155], v[184:187], v[92:95]
	v_mfma_f32_16x16x32_bf16 v[88:91], v[160:163], v[184:187], v[88:91]
	v_mfma_f32_16x16x32_bf16 v[76:79], v[152:155], v[192:195], v[76:79]
	v_mfma_f32_16x16x32_bf16 v[72:75], v[160:163], v[192:195], v[72:75]
	s_setprio 0
	s_barrier
	s_add_i32 s38, 0, 0x1c000
	s_add_i32 s0, s46, s7
	v_add_u32_e32 v151, s38, v147
	v_lshl_add_u64 v[144:145], v[144:145], 0, s[36:37]
	s_mov_b32 m0, s0
	ds_read_b128 v[196:199], v151
	ds_read_b128 v[200:203], v151 offset:1024
	ds_read_b128 v[204:207], v151 offset:2048
	ds_read_b128 v[208:211], v151 offset:3072
	global_load_lds_dwordx4 v[144:145], off
	v_lshl_add_u64 v[144:145], v[212:213], 0, s[36:37]
	s_add_i32 m0, s0, 0x2000
	s_nop 0
	global_load_lds_dwordx4 v[144:145], off
	s_barrier
	s_waitcnt lgkmcnt(0)
	s_setprio 1
	s_waitcnt lgkmcnt(0)
	v_mfma_f32_16x16x32_bf16 v[118:121], v[196:199], v[164:167], v[118:121]
	v_mfma_f32_16x16x32_bf16 v[114:117], v[204:207], v[164:167], v[114:117]
	v_mfma_f32_16x16x32_bf16 v[102:105], v[196:199], v[172:175], v[102:105]
	v_mfma_f32_16x16x32_bf16 v[98:101], v[204:207], v[172:175], v[98:101]
	v_mfma_f32_16x16x32_bf16 v[84:87], v[196:199], v[180:183], v[84:87]
	v_mfma_f32_16x16x32_bf16 v[80:83], v[204:207], v[180:183], v[80:83]
	v_mfma_f32_16x16x32_bf16 v[68:71], v[196:199], v[188:191], v[68:71]
	v_mfma_f32_16x16x32_bf16 v[64:67], v[204:207], v[188:191], v[64:67]
	v_mfma_f32_16x16x32_bf16 v[118:121], v[200:203], v[168:171], v[118:121]
	v_mfma_f32_16x16x32_bf16 v[114:117], v[208:211], v[168:171], v[114:117]
	v_mfma_f32_16x16x32_bf16 v[102:105], v[200:203], v[176:179], v[102:105]
	v_mfma_f32_16x16x32_bf16 v[98:101], v[208:211], v[176:179], v[98:101]
	v_mfma_f32_16x16x32_bf16 v[84:87], v[200:203], v[184:187], v[84:87]
	v_mfma_f32_16x16x32_bf16 v[80:83], v[208:211], v[184:187], v[80:83]
	v_mfma_f32_16x16x32_bf16 v[68:71], v[200:203], v[192:195], v[68:71]
	v_mfma_f32_16x16x32_bf16 v[64:67], v[208:211], v[192:195], v[64:67]
	s_setprio 0
	s_mov_b32 m0, s30
	v_lshl_add_u64 v[144:145], v[214:215], 0, s[36:37]
	s_barrier
	ds_read_b128 v[164:167], v150 offset:49152
	ds_read_b128 v[168:171], v150 offset:50176
	ds_read_b128 v[172:175], v150 offset:51200
	ds_read_b128 v[176:179], v150 offset:52224
	ds_read_b128 v[180:183], v150 offset:53248
	ds_read_b128 v[184:187], v150 offset:54272
	ds_read_b128 v[188:191], v150 offset:55296
	ds_read_b128 v[192:195], v150 offset:56320
	global_load_lds_dwordx4 v[144:145], off
	v_lshl_add_u64 v[144:145], v[216:217], 0, s[36:37]
	s_mov_b32 m0, s31
	s_nop 0
	global_load_lds_dwordx4 v[144:145], off
	s_barrier
; #define LAS __attribute__((address_space(3)))
; DI unsigned pk2(float lo, float hi) { f32x2 v = {lo, hi}; hbf2 r = __builtin_convertvector(v, hbf2); return __builtin_bit_cast(unsigned, r); }
; #define PG8_STAGE(bufoff, gbase, voff) do { _Pragma("unroll") for (int _i = 0; _i < 2; ++_i) \
;         __builtin_amdgcn_global_load_lds((const unsigned*)((const char*)(gbase) + (voff)[_i]), (LAS unsigned*)(lds + (bufoff) + ldsw + _i * 8192), 16, 0, 0); } while (0)
; #define PG8_LDA(dst, b, h) do { _Pragma("unroll") for (int m = 0; m < 4; ++m) _Pragma("unroll") for (int k = 0; k < 2; ++k) dst[m][k] = *(const LAS bf16x8*)(lds + PG8_SA(b, h) + aoff + m * 2048 + k * 1024); } while (0)
; #define PG8_WAIT_V(n) asm volatile("s_waitcnt vmcnt(" #n ")" ::: "memory")
; #define PG8_BAR __builtin_amdgcn_s_barrier()
; template <class Epi, class Sched>
; DI void gemm_phase(LAS unsigned char* lds, const Gemm g, const Sched& S, const Epi& E) {
;     ...
;             PG8_LDA(At, 1, 1); PG8_STAGE(PG8_SA(1, 0), a3, voffA);
;             PG8_BAR; PG8_WAIT_L(0); PG8_MMA(1, 0, At, B0); PG8_BAR; PG8_SCHED;
;             PG8_STAGE(PG8_SB(1, 1), b3 + hstep, voffB);
;             PG8_WAIT_V(6); PG8_BAR; PG8_MMA(1, 1, At, B1); PG8_BAR;
;     DI void operator()(f32x4 (&acc)[2][2][4][2], const Unit& u, int wr, int wc, int fr, int fq, LAS unsigned char* lds) const {
;         const int row0 = u.pm * 256 + wr * 64 + fr, hc = u.pn * 128 + wc * 32 + 8 * fq;
;         float rsv[8];
;         { const LAS float* tab = (const LAS float*)(lds + RS_OFF) + u.rk * 256 + wr * 64 + fr;
; #pragma unroll
;           for (int i = 0; i < 8; ++i) rsv[i] = tab[(i >> 2) * 128 + (i & 3) * 16]; }
; #pragma unroll
;         for (int ai = 0; ai < 2; ++ai)
; #pragma unroll
;             for (int m = 0; m < 4; ++m) {
;                 const int row = row0 + ai * 128 + m * 16; const float rs = rsv[ai * 4 + m];
;                 const f32x4 a0 = acc[ai][0][m][0] * rs, a1 = acc[ai][0][m][1] * rs, b0 = acc[ai][1][m][0] * rs, b1 = acc[ai][1][m][1] * rs;
;                 u32x4 w;
;                 w.x = pk2(silu_mul(a0[0], b0[0]), silu_mul(a0[1], b0[1])); w.y = pk2(silu_mul(a0[2], b0[2]), silu_mul(a0[3], b0[3]));
;                 w.z = pk2(silu_mul(a1[0], b1[0]), silu_mul(a1[1], b1[1])); w.w = pk2(silu_mul(a1[2], b1[2]), silu_mul(a1[3], b1[3]));
;                 *(u32x4*)(H + (size_t)row * DFF + hc) = w;
	s_waitcnt lgkmcnt(0)
	s_setprio 1
	s_waitcnt lgkmcnt(0)
	v_mfma_f32_16x16x32_bf16 v[60:63], v[140:143], v[164:167], v[60:63]
	v_mfma_f32_16x16x32_bf16 v[56:59], v[156:159], v[164:167], v[56:59]
	v_mfma_f32_16x16x32_bf16 v[44:47], v[140:143], v[172:175], v[44:47]
	v_mfma_f32_16x16x32_bf16 v[40:43], v[156:159], v[172:175], v[40:43]
	v_mfma_f32_16x16x32_bf16 v[28:31], v[140:143], v[180:183], v[28:31]
	v_mfma_f32_16x16x32_bf16 v[24:27], v[156:159], v[180:183], v[24:27]
	v_mfma_f32_16x16x32_bf16 v[12:15], v[140:143], v[188:191], v[12:15]
	v_mfma_f32_16x16x32_bf16 v[8:11], v[156:159], v[188:191], v[8:11]
	v_mfma_f32_16x16x32_bf16 v[60:63], v[152:155], v[168:171], v[60:63]
	v_mfma_f32_16x16x32_bf16 v[56:59], v[160:163], v[168:171], v[56:59]
	v_mfma_f32_16x16x32_bf16 v[44:47], v[152:155], v[176:179], v[44:47]
	v_mfma_f32_16x16x32_bf16 v[40:43], v[160:163], v[176:179], v[40:43]
	v_mfma_f32_16x16x32_bf16 v[28:31], v[152:155], v[184:187], v[28:31]
	v_mfma_f32_16x16x32_bf16 v[24:27], v[160:163], v[184:187], v[24:27]
	v_mfma_f32_16x16x32_bf16 v[12:15], v[152:155], v[192:195], v[12:15]
	v_mfma_f32_16x16x32_bf16 v[8:11], v[160:163], v[192:195], v[8:11]
	s_setprio 0
	s_barrier
	s_add_u32 s0, s24, 0x40080
	s_addc_u32 s1, s25, 0
	s_add_i32 s24, s38, s7
	v_lshl_add_u64 v[140:141], s[0:1], 0, v[96:97]
	s_mov_b32 m0, s24
	s_nop 0
	global_load_lds_dwordx4 v[140:141], off
	v_lshl_add_u64 v[140:141], s[0:1], 0, v[134:135]
	s_add_i32 m0, s24, 0x2000
	s_nop 0
	global_load_lds_dwordx4 v[140:141], off
	s_waitcnt vmcnt(6)
	s_barrier
	s_setprio 1
	v_mfma_f32_16x16x32_bf16 v[52:55], v[196:199], v[164:167], v[52:55]
	v_mfma_f32_16x16x32_bf16 v[48:51], v[204:207], v[164:167], v[48:51]
	v_mfma_f32_16x16x32_bf16 v[36:39], v[196:199], v[172:175], v[36:39]
	v_mfma_f32_16x16x32_bf16 v[32:35], v[204:207], v[172:175], v[32:35]
	v_mfma_f32_16x16x32_bf16 v[20:23], v[196:199], v[180:183], v[20:23]
	v_mfma_f32_16x16x32_bf16 v[16:19], v[204:207], v[180:183], v[16:19]
	v_mfma_f32_16x16x32_bf16 v[4:7], v[196:199], v[188:191], v[4:7]
	v_mfma_f32_16x16x32_bf16 v[0:3], v[204:207], v[188:191], v[0:3]
	v_mfma_f32_16x16x32_bf16 v[52:55], v[200:203], v[168:171], v[52:55]
	v_mfma_f32_16x16x32_bf16 v[48:51], v[208:211], v[168:171], v[48:51]
	v_mfma_f32_16x16x32_bf16 v[36:39], v[200:203], v[176:179], v[36:39]
	v_mfma_f32_16x16x32_bf16 v[32:35], v[208:211], v[176:179], v[32:35]
	v_mfma_f32_16x16x32_bf16 v[20:23], v[200:203], v[184:187], v[20:23]
	v_mfma_f32_16x16x32_bf16 v[16:19], v[208:211], v[184:187], v[16:19]
	v_mfma_f32_16x16x32_bf16 v[4:7], v[200:203], v[192:195], v[4:7]
	v_mfma_f32_16x16x32_bf16 v[0:3], v[208:211], v[192:195], v[0:3]
	s_setprio 0
	s_add_i32 s45, s45, 2
	s_add_u32 s22, s22, 0x100
	s_addc_u32 s23, s23, 0
	s_add_u32 s43, s43, 0x100
	s_addc_u32 s44, s44, 0
	s_cmp_lt_u32 s45, 14
	s_barrier
	s_cbranch_scc1 .LBB0_1840
	v_lshl_add_u32 v140, s33, 10, v148
	ds_read2_b32 v[152:153], v140 offset1:16
	ds_read2_b32 v[144:145], v140 offset0:32 offset1:48
	ds_read2_b32 v[142:143], v140 offset0:128 offset1:144
	ds_read2_b32 v[140:141], v140 offset0:160 offset1:176
	v_lshl_or_b32 v154, s2, 7, v149
	v_lshl_add_u32 v151, s41, 8, v146
	v_lshlrev_b32_e32 v154, 1, v154
	v_mad_u32_u24 v155, v151, s35, v154
	s_mov_b64 s[22:23], -1
	s_andn2_b64 vcc, exec, s[16:17]
	s_waitcnt lgkmcnt(0)
	v_pk_mul_f32 v[126:127], v[126:127], v[152:153] op_sel_hi:[1,0]
	v_pk_mul_f32 v[128:129], v[128:129], v[152:153] op_sel_hi:[1,0]
	v_pk_mul_f32 v[122:123], v[122:123], v[152:153] op_sel_hi:[1,0]
	v_pk_mul_f32 v[124:125], v[124:125], v[152:153] op_sel_hi:[1,0]
	v_pk_mul_f32 v[118:119], v[118:119], v[152:153] op_sel_hi:[1,0]
	v_pk_mul_f32 v[120:121], v[120:121], v[152:153] op_sel_hi:[1,0]
	v_pk_mul_f32 v[114:115], v[114:115], v[152:153] op_sel_hi:[1,0]
	v_pk_mul_f32 v[116:117], v[116:117], v[152:153] op_sel_hi:[1,0]
	v_mul_f32_e32 v156, 0xbfb8aa3b, v126
	v_mul_f32_e32 v157, 0xbfb8aa3b, v127
	v_mul_f32_e32 v158, 0xbfb8aa3b, v128
	v_mul_f32_e32 v159, 0xbfb8aa3b, v129
	v_mul_f32_e32 v160, 0xbfb8aa3b, v122
	v_mul_f32_e32 v161, 0xbfb8aa3b, v123
	v_mul_f32_e32 v162, 0xbfb8aa3b, v124
	v_mul_f32_e32 v163, 0xbfb8aa3b, v125
	v_exp_f32_e32 v156, v156
	v_exp_f32_e32 v157, v157
	v_exp_f32_e32 v158, v158
	v_exp_f32_e32 v159, v159
	v_exp_f32_e32 v160, v160
	v_exp_f32_e32 v161, v161
	v_exp_f32_e32 v162, v162
	v_exp_f32_e32 v163, v163
	v_add_f32_e32 v156, 1.0, v156
	v_add_f32_e32 v157, 1.0, v157
	v_add_f32_e32 v158, 1.0, v158
	v_add_f32_e32 v159, 1.0, v159
	v_add_f32_e32 v160, 1.0, v160
	v_add_f32_e32 v161, 1.0, v161
	v_add_f32_e32 v162, 1.0, v162
	v_add_f32_e32 v163, 1.0, v163
	v_rcp_f32_e32 v156, v156
	v_rcp_f32_e32 v157, v157
	v_rcp_f32_e32 v158, v158
	v_rcp_f32_e32 v159, v159
	v_rcp_f32_e32 v160, v160
	v_rcp_f32_e32 v161, v161
	v_rcp_f32_e32 v162, v162
	v_rcp_f32_e32 v163, v163
	v_add_u32_e32 v172, 0x0, v155
	v_pk_mul_f32 v[126:127], v[126:127], v[156:157]
	v_pk_mul_f32 v[128:129], v[128:129], v[158:159]
	v_pk_mul_f32 v[122:123], v[122:123], v[160:161]
	v_pk_mul_f32 v[124:125], v[124:125], v[162:163]
	v_pk_mul_f32 v[118:119], v[118:119], v[126:127]
	v_pk_mul_f32 v[120:121], v[120:121], v[128:129]
	v_pk_mul_f32 v[114:115], v[114:115], v[122:123]
	v_pk_mul_f32 v[116:117], v[116:117], v[124:125]
	v_cvt_pk_bf16_f32 v164, v118, v119
	v_cvt_pk_bf16_f32 v165, v120, v121
	v_cvt_pk_bf16_f32 v166, v114, v115
	v_cvt_pk_bf16_f32 v167, v116, v117
	global_store_dwordx4 v172, v[164:167], s[74:75]
	v_pk_mul_f32 v[110:111], v[110:111], v[152:153] op_sel:[0,1]
	v_pk_mul_f32 v[112:113], v[112:113], v[152:153] op_sel:[0,1]
	v_pk_mul_f32 v[106:107], v[106:107], v[152:153] op_sel:[0,1]
	v_pk_mul_f32 v[108:109], v[108:109], v[152:153] op_sel:[0,1]
; DI unsigned pk2(float lo, float hi) { f32x2 v = {lo, hi}; hbf2 r = __builtin_convertvector(v, hbf2); return __builtin_bit_cast(unsigned, r); }
; DI float silu_mul(float a, float b) { return a * fast_rcp(1.0f + fast_exp2(-a * LOG2E)) * b; }
;     DI void operator()(f32x4 (&acc)[2][2][4][2], const Unit& u, int wr, int wc, int fr, int fq, LAS unsigned char* lds) const {
;     ...
;         for (int ai = 0; ai < 2; ++ai)
; #pragma unroll
;             for (int m = 0; m < 4; ++m) {
;                 const int row = row0 + ai * 128 + m * 16; const float rs = rsv[ai * 4 + m];
;                 const f32x4 a0 = acc[ai][0][m][0] * rs, a1 = acc[ai][0][m][1] * rs, b0 = acc[ai][1][m][0] * rs, b1 = acc[ai][1][m][1] * rs;
;                 u32x4 w;
;                 w.x = pk2(silu_mul(a0[0], b0[0]), silu_mul(a0[1], b0[1])); w.y = pk2(silu_mul(a0[2], b0[2]), silu_mul(a0[3], b0[3]));
;                 w.z = pk2(silu_mul(a1[0], b1[0]), silu_mul(a1[1], b1[1])); w.w = pk2(silu_mul(a1[2], b1[2]), silu_mul(a1[3], b1[3]));
;                 *(u32x4*)(H + (size_t)row * DFF + hc) = w;
	v_pk_mul_f32 v[102:103], v[102:103], v[152:153] op_sel:[0,1]
	v_pk_mul_f32 v[104:105], v[104:105], v[152:153] op_sel:[0,1]
	v_pk_mul_f32 v[98:99], v[98:99], v[152:153] op_sel:[0,1]
	v_pk_mul_f32 v[100:101], v[100:101], v[152:153] op_sel:[0,1]
	v_mul_f32_e32 v156, 0xbfb8aa3b, v110
	v_mul_f32_e32 v157, 0xbfb8aa3b, v111
	v_mul_f32_e32 v158, 0xbfb8aa3b, v112
	v_mul_f32_e32 v159, 0xbfb8aa3b, v113
	v_mul_f32_e32 v160, 0xbfb8aa3b, v106
	v_mul_f32_e32 v161, 0xbfb8aa3b, v107
	v_mul_f32_e32 v162, 0xbfb8aa3b, v108
	v_mul_f32_e32 v163, 0xbfb8aa3b, v109
	v_exp_f32_e32 v156, v156
	v_exp_f32_e32 v157, v157
	v_exp_f32_e32 v158, v158
	v_exp_f32_e32 v159, v159
	v_exp_f32_e32 v160, v160
	v_exp_f32_e32 v161, v161
	v_exp_f32_e32 v162, v162
	v_exp_f32_e32 v163, v163
	v_add_f32_e32 v156, 1.0, v156
	v_add_f32_e32 v157, 1.0, v157
	v_add_f32_e32 v158, 1.0, v158
	v_add_f32_e32 v159, 1.0, v159
	v_add_f32_e32 v160, 1.0, v160
	v_add_f32_e32 v161, 1.0, v161
	v_add_f32_e32 v162, 1.0, v162
	v_add_f32_e32 v163, 1.0, v163
	v_rcp_f32_e32 v156, v156
	v_rcp_f32_e32 v157, v157
	v_rcp_f32_e32 v158, v158
	v_rcp_f32_e32 v159, v159
	v_rcp_f32_e32 v160, v160
	v_rcp_f32_e32 v161, v161
	v_rcp_f32_e32 v162, v162
	v_rcp_f32_e32 v163, v163
	v_add_u32_e32 v172, 0x16000, v155
	v_pk_mul_f32 v[110:111], v[110:111], v[156:157]
	v_pk_mul_f32 v[112:113], v[112:113], v[158:159]
	v_pk_mul_f32 v[106:107], v[106:107], v[160:161]
	v_pk_mul_f32 v[108:109], v[108:109], v[162:163]
	v_pk_mul_f32 v[102:103], v[102:103], v[110:111]
	v_pk_mul_f32 v[104:105], v[104:105], v[112:113]
	v_pk_mul_f32 v[98:99], v[98:99], v[106:107]
	v_pk_mul_f32 v[100:101], v[100:101], v[108:109]
	v_cvt_pk_bf16_f32 v168, v102, v103
	v_cvt_pk_bf16_f32 v169, v104, v105
	v_cvt_pk_bf16_f32 v170, v98, v99
	v_cvt_pk_bf16_f32 v171, v100, v101
	global_store_dwordx4 v172, v[168:171], s[74:75]
	v_pk_mul_f32 v[92:93], v[92:93], v[144:145] op_sel_hi:[1,0]
	v_pk_mul_f32 v[94:95], v[94:95], v[144:145] op_sel_hi:[1,0]
	v_pk_mul_f32 v[88:89], v[88:89], v[144:145] op_sel_hi:[1,0]
	v_pk_mul_f32 v[90:91], v[90:91], v[144:145] op_sel_hi:[1,0]
	v_pk_mul_f32 v[84:85], v[84:85], v[144:145] op_sel_hi:[1,0]
	v_pk_mul_f32 v[86:87], v[86:87], v[144:145] op_sel_hi:[1,0]
	v_pk_mul_f32 v[80:81], v[80:81], v[144:145] op_sel_hi:[1,0]
	v_pk_mul_f32 v[82:83], v[82:83], v[144:145] op_sel_hi:[1,0]
	v_mul_f32_e32 v156, 0xbfb8aa3b, v92
	v_mul_f32_e32 v157, 0xbfb8aa3b, v93
	v_mul_f32_e32 v158, 0xbfb8aa3b, v94
	v_mul_f32_e32 v159, 0xbfb8aa3b, v95
	v_mul_f32_e32 v160, 0xbfb8aa3b, v88
	v_mul_f32_e32 v161, 0xbfb8aa3b, v89
	v_mul_f32_e32 v162, 0xbfb8aa3b, v90
	v_mul_f32_e32 v163, 0xbfb8aa3b, v91
	v_exp_f32_e32 v156, v156
	v_exp_f32_e32 v157, v157
	v_exp_f32_e32 v158, v158
	v_exp_f32_e32 v159, v159
	v_exp_f32_e32 v160, v160
	v_exp_f32_e32 v161, v161
	v_exp_f32_e32 v162, v162
	v_exp_f32_e32 v163, v163
	v_add_f32_e32 v156, 1.0, v156
	v_add_f32_e32 v157, 1.0, v157
	v_add_f32_e32 v158, 1.0, v158
	v_add_f32_e32 v159, 1.0, v159
	v_add_f32_e32 v160, 1.0, v160
	v_add_f32_e32 v161, 1.0, v161
	v_add_f32_e32 v162, 1.0, v162
	v_add_f32_e32 v163, 1.0, v163
	v_rcp_f32_e32 v156, v156
	v_rcp_f32_e32 v157, v157
	v_rcp_f32_e32 v158, v158
	v_rcp_f32_e32 v159, v159
	v_rcp_f32_e32 v160, v160
	v_rcp_f32_e32 v161, v161
	v_rcp_f32_e32 v162, v162
	v_rcp_f32_e32 v163, v163
	v_add_u32_e32 v172, 0x2c000, v155
	v_pk_mul_f32 v[92:93], v[92:93], v[156:157]
	v_pk_mul_f32 v[94:95], v[94:95], v[158:159]
	v_pk_mul_f32 v[88:89], v[88:89], v[160:161]
	v_pk_mul_f32 v[90:91], v[90:91], v[162:163]
	v_pk_mul_f32 v[84:85], v[84:85], v[92:93]
	v_pk_mul_f32 v[86:87], v[86:87], v[94:95]
	v_pk_mul_f32 v[80:81], v[80:81], v[88:89]
	v_pk_mul_f32 v[82:83], v[82:83], v[90:91]
	v_cvt_pk_bf16_f32 v164, v84, v85
	v_cvt_pk_bf16_f32 v165, v86, v87
	v_cvt_pk_bf16_f32 v166, v80, v81
	v_cvt_pk_bf16_f32 v167, v82, v83
	global_store_dwordx4 v172, v[164:167], s[74:75]
	v_pk_mul_f32 v[76:77], v[76:77], v[144:145] op_sel:[0,1]
	v_pk_mul_f32 v[78:79], v[78:79], v[144:145] op_sel:[0,1]
	v_pk_mul_f32 v[72:73], v[72:73], v[144:145] op_sel:[0,1]
	v_pk_mul_f32 v[74:75], v[74:75], v[144:145] op_sel:[0,1]
	v_pk_mul_f32 v[68:69], v[68:69], v[144:145] op_sel:[0,1]
	v_pk_mul_f32 v[70:71], v[70:71], v[144:145] op_sel:[0,1]
	v_pk_mul_f32 v[64:65], v[64:65], v[144:145] op_sel:[0,1]
	v_pk_mul_f32 v[66:67], v[66:67], v[144:145] op_sel:[0,1]
	v_mul_f32_e32 v156, 0xbfb8aa3b, v76
	v_mul_f32_e32 v157, 0xbfb8aa3b, v77
	v_mul_f32_e32 v158, 0xbfb8aa3b, v78
	v_mul_f32_e32 v159, 0xbfb8aa3b, v79
	v_mul_f32_e32 v160, 0xbfb8aa3b, v72
	v_mul_f32_e32 v161, 0xbfb8aa3b, v73
	v_mul_f32_e32 v162, 0xbfb8aa3b, v74
	v_mul_f32_e32 v163, 0xbfb8aa3b, v75
	v_exp_f32_e32 v156, v156
	v_exp_f32_e32 v157, v157
	v_exp_f32_e32 v158, v158
	v_exp_f32_e32 v159, v159
	v_exp_f32_e32 v160, v160
	v_exp_f32_e32 v161, v161
	v_exp_f32_e32 v162, v162
	v_exp_f32_e32 v163, v163
	v_add_f32_e32 v156, 1.0, v156
	v_add_f32_e32 v157, 1.0, v157
	v_add_f32_e32 v158, 1.0, v158
	v_add_f32_e32 v159, 1.0, v159
	v_add_f32_e32 v160, 1.0, v160
	v_add_f32_e32 v161, 1.0, v161
	v_add_f32_e32 v162, 1.0, v162
	v_add_f32_e32 v163, 1.0, v163
	v_rcp_f32_e32 v156, v156
	v_rcp_f32_e32 v157, v157
	v_rcp_f32_e32 v158, v158
	v_rcp_f32_e32 v159, v159
	v_rcp_f32_e32 v160, v160
	v_rcp_f32_e32 v161, v161
	v_rcp_f32_e32 v162, v162
	v_rcp_f32_e32 v163, v163
	v_add_u32_e32 v172, 0x42000, v155
	v_pk_mul_f32 v[76:77], v[76:77], v[156:157]
	v_pk_mul_f32 v[78:79], v[78:79], v[158:159]
	v_pk_mul_f32 v[72:73], v[72:73], v[160:161]
	v_pk_mul_f32 v[74:75], v[74:75], v[162:163]
	v_pk_mul_f32 v[68:69], v[68:69], v[76:77]
	v_pk_mul_f32 v[70:71], v[70:71], v[78:79]
	v_pk_mul_f32 v[64:65], v[64:65], v[72:73]
	v_pk_mul_f32 v[66:67], v[66:67], v[74:75]
; DI unsigned pk2(float lo, float hi) { f32x2 v = {lo, hi}; hbf2 r = __builtin_convertvector(v, hbf2); return __builtin_bit_cast(unsigned, r); }
; DI float silu_mul(float a, float b) { return a * fast_rcp(1.0f + fast_exp2(-a * LOG2E)) * b; }
;     DI void operator()(f32x4 (&acc)[2][2][4][2], const Unit& u, int wr, int wc, int fr, int fq, LAS unsigned char* lds) const {
;     ...
;         for (int ai = 0; ai < 2; ++ai)
; #pragma unroll
;             for (int m = 0; m < 4; ++m) {
;                 const int row = row0 + ai * 128 + m * 16; const float rs = rsv[ai * 4 + m];
;                 const f32x4 a0 = acc[ai][0][m][0] * rs, a1 = acc[ai][0][m][1] * rs, b0 = acc[ai][1][m][0] * rs, b1 = acc[ai][1][m][1] * rs;
;                 u32x4 w;
;                 w.x = pk2(silu_mul(a0[0], b0[0]), silu_mul(a0[1], b0[1])); w.y = pk2(silu_mul(a0[2], b0[2]), silu_mul(a0[3], b0[3]));
;                 w.z = pk2(silu_mul(a1[0], b1[0]), silu_mul(a1[1], b1[1])); w.w = pk2(silu_mul(a1[2], b1[2]), silu_mul(a1[3], b1[3]));
;                 *(u32x4*)(H + (size_t)row * DFF + hc) = w;
	v_cvt_pk_bf16_f32 v168, v68, v69
	v_cvt_pk_bf16_f32 v169, v70, v71
	v_cvt_pk_bf16_f32 v170, v64, v65
	v_cvt_pk_bf16_f32 v171, v66, v67
	global_store_dwordx4 v172, v[168:171], s[74:75]
	v_pk_mul_f32 v[60:61], v[60:61], v[142:143] op_sel_hi:[1,0]
	v_pk_mul_f32 v[62:63], v[62:63], v[142:143] op_sel_hi:[1,0]
	v_pk_mul_f32 v[56:57], v[56:57], v[142:143] op_sel_hi:[1,0]
	v_pk_mul_f32 v[58:59], v[58:59], v[142:143] op_sel_hi:[1,0]
	v_pk_mul_f32 v[52:53], v[52:53], v[142:143] op_sel_hi:[1,0]
	v_pk_mul_f32 v[54:55], v[54:55], v[142:143] op_sel_hi:[1,0]
	v_pk_mul_f32 v[48:49], v[48:49], v[142:143] op_sel_hi:[1,0]
	v_pk_mul_f32 v[50:51], v[50:51], v[142:143] op_sel_hi:[1,0]
	v_mul_f32_e32 v156, 0xbfb8aa3b, v60
	v_mul_f32_e32 v157, 0xbfb8aa3b, v61
	v_mul_f32_e32 v158, 0xbfb8aa3b, v62
	v_mul_f32_e32 v159, 0xbfb8aa3b, v63
	v_mul_f32_e32 v160, 0xbfb8aa3b, v56
	v_mul_f32_e32 v161, 0xbfb8aa3b, v57
	v_mul_f32_e32 v162, 0xbfb8aa3b, v58
	v_mul_f32_e32 v163, 0xbfb8aa3b, v59
	v_exp_f32_e32 v156, v156
	v_exp_f32_e32 v157, v157
	v_exp_f32_e32 v158, v158
	v_exp_f32_e32 v159, v159
	v_exp_f32_e32 v160, v160
	v_exp_f32_e32 v161, v161
	v_exp_f32_e32 v162, v162
	v_exp_f32_e32 v163, v163
	v_add_f32_e32 v156, 1.0, v156
	v_add_f32_e32 v157, 1.0, v157
	v_add_f32_e32 v158, 1.0, v158
	v_add_f32_e32 v159, 1.0, v159
	v_add_f32_e32 v160, 1.0, v160
	v_add_f32_e32 v161, 1.0, v161
	v_add_f32_e32 v162, 1.0, v162
	v_add_f32_e32 v163, 1.0, v163
	v_rcp_f32_e32 v156, v156
	v_rcp_f32_e32 v157, v157
	v_rcp_f32_e32 v158, v158
	v_rcp_f32_e32 v159, v159
	v_rcp_f32_e32 v160, v160
	v_rcp_f32_e32 v161, v161
	v_rcp_f32_e32 v162, v162
	v_rcp_f32_e32 v163, v163
	v_add_u32_e32 v172, 0xb0000, v155
	v_pk_mul_f32 v[60:61], v[60:61], v[156:157]
	v_pk_mul_f32 v[62:63], v[62:63], v[158:159]
	v_pk_mul_f32 v[56:57], v[56:57], v[160:161]
	v_pk_mul_f32 v[58:59], v[58:59], v[162:163]
	v_pk_mul_f32 v[52:53], v[52:53], v[60:61]
	v_pk_mul_f32 v[54:55], v[54:55], v[62:63]
	v_pk_mul_f32 v[48:49], v[48:49], v[56:57]
	v_pk_mul_f32 v[50:51], v[50:51], v[58:59]
	v_cvt_pk_bf16_f32 v164, v52, v53
	v_cvt_pk_bf16_f32 v165, v54, v55
	v_cvt_pk_bf16_f32 v166, v48, v49
	v_cvt_pk_bf16_f32 v167, v50, v51
	global_store_dwordx4 v172, v[164:167], s[74:75]
	v_pk_mul_f32 v[44:45], v[44:45], v[142:143] op_sel:[0,1]
	v_pk_mul_f32 v[46:47], v[46:47], v[142:143] op_sel:[0,1]
	v_pk_mul_f32 v[40:41], v[40:41], v[142:143] op_sel:[0,1]
	v_pk_mul_f32 v[42:43], v[42:43], v[142:143] op_sel:[0,1]
	v_pk_mul_f32 v[36:37], v[36:37], v[142:143] op_sel:[0,1]
	v_pk_mul_f32 v[38:39], v[38:39], v[142:143] op_sel:[0,1]
	v_pk_mul_f32 v[32:33], v[32:33], v[142:143] op_sel:[0,1]
	v_pk_mul_f32 v[34:35], v[34:35], v[142:143] op_sel:[0,1]
	v_mul_f32_e32 v156, 0xbfb8aa3b, v44
	v_mul_f32_e32 v157, 0xbfb8aa3b, v45
	v_mul_f32_e32 v158, 0xbfb8aa3b, v46
	v_mul_f32_e32 v159, 0xbfb8aa3b, v47
	v_mul_f32_e32 v160, 0xbfb8aa3b, v40
	v_mul_f32_e32 v161, 0xbfb8aa3b, v41
	v_mul_f32_e32 v162, 0xbfb8aa3b, v42
	v_mul_f32_e32 v163, 0xbfb8aa3b, v43
	v_exp_f32_e32 v156, v156
	v_exp_f32_e32 v157, v157
	v_exp_f32_e32 v158, v158
	v_exp_f32_e32 v159, v159
	v_exp_f32_e32 v160, v160
	v_exp_f32_e32 v161, v161
	v_exp_f32_e32 v162, v162
	v_exp_f32_e32 v163, v163
	v_add_f32_e32 v156, 1.0, v156
	v_add_f32_e32 v157, 1.0, v157
	v_add_f32_e32 v158, 1.0, v158
	v_add_f32_e32 v159, 1.0, v159
	v_add_f32_e32 v160, 1.0, v160
	v_add_f32_e32 v161, 1.0, v161
	v_add_f32_e32 v162, 1.0, v162
	v_add_f32_e32 v163, 1.0, v163
	v_rcp_f32_e32 v156, v156
	v_rcp_f32_e32 v157, v157
	v_rcp_f32_e32 v158, v158
	v_rcp_f32_e32 v159, v159
	v_rcp_f32_e32 v160, v160
	v_rcp_f32_e32 v161, v161
	v_rcp_f32_e32 v162, v162
	v_rcp_f32_e32 v163, v163
	v_add_u32_e32 v172, 0xc6000, v155
	v_pk_mul_f32 v[44:45], v[44:45], v[156:157]
	v_pk_mul_f32 v[46:47], v[46:47], v[158:159]
	v_pk_mul_f32 v[40:41], v[40:41], v[160:161]
	v_pk_mul_f32 v[42:43], v[42:43], v[162:163]
	v_pk_mul_f32 v[36:37], v[36:37], v[44:45]
	v_pk_mul_f32 v[38:39], v[38:39], v[46:47]
	v_pk_mul_f32 v[32:33], v[32:33], v[40:41]
	v_pk_mul_f32 v[34:35], v[34:35], v[42:43]
	v_cvt_pk_bf16_f32 v168, v36, v37
	v_cvt_pk_bf16_f32 v169, v38, v39
	v_cvt_pk_bf16_f32 v170, v32, v33
	v_cvt_pk_bf16_f32 v171, v34, v35
; DI unsigned pk2(float lo, float hi) { f32x2 v = {lo, hi}; hbf2 r = __builtin_convertvector(v, hbf2); return __builtin_bit_cast(unsigned, r); }
; DI float silu_mul(float a, float b) { return a * fast_rcp(1.0f + fast_exp2(-a * LOG2E)) * b; }
; template <class Epi, class Sched>
; DI void gemm_phase(LAS unsigned char* lds, const Gemm g, const Sched& S, const Epi& E) {
;     ...
;         nxt.rk = cur.rk + (nxt.pm != cur.pm ? 1 : 0);
;     DI void operator()(f32x4 (&acc)[2][2][4][2], const Unit& u, int wr, int wc, int fr, int fq, LAS unsigned char* lds) const {
;     ...
;         for (int ai = 0; ai < 2; ++ai)
; #pragma unroll
;             for (int m = 0; m < 4; ++m) {
;                 const int row = row0 + ai * 128 + m * 16; const float rs = rsv[ai * 4 + m];
;                 const f32x4 a0 = acc[ai][0][m][0] * rs, a1 = acc[ai][0][m][1] * rs, b0 = acc[ai][1][m][0] * rs, b1 = acc[ai][1][m][1] * rs;
;                 u32x4 w;
;                 w.x = pk2(silu_mul(a0[0], b0[0]), silu_mul(a0[1], b0[1])); w.y = pk2(silu_mul(a0[2], b0[2]), silu_mul(a0[3], b0[3]));
;                 w.z = pk2(silu_mul(a1[0], b1[0]), silu_mul(a1[1], b1[1])); w.w = pk2(silu_mul(a1[2], b1[2]), silu_mul(a1[3], b1[3]));
;                 *(u32x4*)(H + (size_t)row * DFF + hc) = w;
	global_store_dwordx4 v172, v[168:171], s[74:75]
	v_pk_mul_f32 v[28:29], v[28:29], v[140:141] op_sel_hi:[1,0]
	v_pk_mul_f32 v[30:31], v[30:31], v[140:141] op_sel_hi:[1,0]
	v_pk_mul_f32 v[24:25], v[24:25], v[140:141] op_sel_hi:[1,0]
	v_pk_mul_f32 v[26:27], v[26:27], v[140:141] op_sel_hi:[1,0]
	v_pk_mul_f32 v[20:21], v[20:21], v[140:141] op_sel_hi:[1,0]
	v_pk_mul_f32 v[22:23], v[22:23], v[140:141] op_sel_hi:[1,0]
	v_pk_mul_f32 v[16:17], v[16:17], v[140:141] op_sel_hi:[1,0]
	v_pk_mul_f32 v[18:19], v[18:19], v[140:141] op_sel_hi:[1,0]
	v_mul_f32_e32 v156, 0xbfb8aa3b, v28
	v_mul_f32_e32 v157, 0xbfb8aa3b, v29
	v_mul_f32_e32 v158, 0xbfb8aa3b, v30
	v_mul_f32_e32 v159, 0xbfb8aa3b, v31
	v_mul_f32_e32 v160, 0xbfb8aa3b, v24
	v_mul_f32_e32 v161, 0xbfb8aa3b, v25
	v_mul_f32_e32 v162, 0xbfb8aa3b, v26
	v_mul_f32_e32 v163, 0xbfb8aa3b, v27
	v_exp_f32_e32 v156, v156
	v_exp_f32_e32 v157, v157
	v_exp_f32_e32 v158, v158
	v_exp_f32_e32 v159, v159
	v_exp_f32_e32 v160, v160
	v_exp_f32_e32 v161, v161
	v_exp_f32_e32 v162, v162
	v_exp_f32_e32 v163, v163
	v_add_f32_e32 v156, 1.0, v156
	v_add_f32_e32 v157, 1.0, v157
	v_add_f32_e32 v158, 1.0, v158
	v_add_f32_e32 v159, 1.0, v159
	v_add_f32_e32 v160, 1.0, v160
	v_add_f32_e32 v161, 1.0, v161
	v_add_f32_e32 v162, 1.0, v162
	v_add_f32_e32 v163, 1.0, v163
	v_rcp_f32_e32 v156, v156
	v_rcp_f32_e32 v157, v157
	v_rcp_f32_e32 v158, v158
	v_rcp_f32_e32 v159, v159
	v_rcp_f32_e32 v160, v160
	v_rcp_f32_e32 v161, v161
	v_rcp_f32_e32 v162, v162
	v_rcp_f32_e32 v163, v163
	v_add_u32_e32 v172, 0xdc000, v155
	v_pk_mul_f32 v[28:29], v[28:29], v[156:157]
	v_pk_mul_f32 v[30:31], v[30:31], v[158:159]
	v_pk_mul_f32 v[24:25], v[24:25], v[160:161]
	v_pk_mul_f32 v[26:27], v[26:27], v[162:163]
	v_pk_mul_f32 v[20:21], v[20:21], v[28:29]
	v_pk_mul_f32 v[22:23], v[22:23], v[30:31]
	v_pk_mul_f32 v[16:17], v[16:17], v[24:25]
	v_pk_mul_f32 v[18:19], v[18:19], v[26:27]
	v_cvt_pk_bf16_f32 v164, v20, v21
	v_cvt_pk_bf16_f32 v165, v22, v23
	v_cvt_pk_bf16_f32 v166, v16, v17
	v_cvt_pk_bf16_f32 v167, v18, v19
	global_store_dwordx4 v172, v[164:167], s[74:75]
	v_pk_mul_f32 v[12:13], v[12:13], v[140:141] op_sel:[0,1]
	v_pk_mul_f32 v[14:15], v[14:15], v[140:141] op_sel:[0,1]
	v_pk_mul_f32 v[8:9], v[8:9], v[140:141] op_sel:[0,1]
	v_pk_mul_f32 v[10:11], v[10:11], v[140:141] op_sel:[0,1]
	v_pk_mul_f32 v[4:5], v[4:5], v[140:141] op_sel:[0,1]
	v_pk_mul_f32 v[6:7], v[6:7], v[140:141] op_sel:[0,1]
	v_pk_mul_f32 v[0:1], v[0:1], v[140:141] op_sel:[0,1]
	v_pk_mul_f32 v[2:3], v[2:3], v[140:141] op_sel:[0,1]
	v_mul_f32_e32 v156, 0xbfb8aa3b, v12
	v_mul_f32_e32 v157, 0xbfb8aa3b, v13
	v_mul_f32_e32 v158, 0xbfb8aa3b, v14
	v_mul_f32_e32 v159, 0xbfb8aa3b, v15
	v_mul_f32_e32 v160, 0xbfb8aa3b, v8
	v_mul_f32_e32 v161, 0xbfb8aa3b, v9
	v_mul_f32_e32 v162, 0xbfb8aa3b, v10
	v_mul_f32_e32 v163, 0xbfb8aa3b, v11
	v_exp_f32_e32 v156, v156
	v_exp_f32_e32 v157, v157
	v_exp_f32_e32 v158, v158
	v_exp_f32_e32 v159, v159
	v_exp_f32_e32 v160, v160
	v_exp_f32_e32 v161, v161
	v_exp_f32_e32 v162, v162
	v_exp_f32_e32 v163, v163
	v_add_f32_e32 v156, 1.0, v156
	v_add_f32_e32 v157, 1.0, v157
	v_add_f32_e32 v158, 1.0, v158
	v_add_f32_e32 v159, 1.0, v159
	v_add_f32_e32 v160, 1.0, v160
	v_add_f32_e32 v161, 1.0, v161
	v_add_f32_e32 v162, 1.0, v162
	v_add_f32_e32 v163, 1.0, v163
	v_rcp_f32_e32 v156, v156
	v_rcp_f32_e32 v157, v157
	v_rcp_f32_e32 v158, v158
	v_rcp_f32_e32 v159, v159
	v_rcp_f32_e32 v160, v160
	v_rcp_f32_e32 v161, v161
	v_rcp_f32_e32 v162, v162
	v_rcp_f32_e32 v163, v163
	v_add_u32_e32 v172, 0xf2000, v155
	v_pk_mul_f32 v[12:13], v[12:13], v[156:157]
	v_pk_mul_f32 v[14:15], v[14:15], v[158:159]
	v_pk_mul_f32 v[8:9], v[8:9], v[160:161]
	v_pk_mul_f32 v[10:11], v[10:11], v[162:163]
	v_pk_mul_f32 v[4:5], v[4:5], v[12:13]
	v_pk_mul_f32 v[6:7], v[6:7], v[14:15]
	v_pk_mul_f32 v[0:1], v[0:1], v[8:9]
	v_pk_mul_f32 v[2:3], v[2:3], v[10:11]
	v_cvt_pk_bf16_f32 v168, v4, v5
	v_cvt_pk_bf16_f32 v169, v6, v7
	v_cvt_pk_bf16_f32 v170, v0, v1
	v_cvt_pk_bf16_f32 v171, v2, v3
	global_store_dwordx4 v172, v[168:171], s[74:75]
	s_cbranch_vccnz .LBB0_1831
	s_cmp_lg_u32 s14, s41
	s_cselect_b64 s[0:1], -1, 0
	s_cmp_lg_u64 s[0:1], 0
	s_addc_u32 s33, s33, 0
	s_mov_b64 s[22:23], 0
	s_branch .LBB0_1831
